# In and Up sample-row small GEMM K-loops also software-pipelined two K-steps deep (second staging register set)
# baseline (speedup 1.0000x reference)
;     ...
;         for (int i = 0; i < 16; ++i) { acc0[i] = 0.f; acc1[i] = 0.f; }
;         float q8[8];
; #pragma unroll
;         for (int i = 0; i < 8; ++i) q8[i] = 0.f;
;         int rb = 0, cg = 0;
;         if (act) {
;             rb = task / ncg; cg = task - rb * ncg;
;             const int Kw = K / KS, nb = Kw / 64, k0 = ks * Kw;
;             const bf16_t* b0p = Bt + (size_t)(E.brow(cg, 0) + (lane >> 3)) * K + k0 + 8 * (lane & 7);
;             const bf16_t* b1p = Bt + (size_t)(E.brow(cg, 1) + (lane >> 3)) * K + k0 + 8 * (lane & 7);
;             const float* afp = (const float*)Abase + (size_t)(32 * rb + (lane >> 4)) * K + k0 + 4 * (lane & 15);
;             const bf16_t* abp = (const bf16_t*)Abase + (size_t)(32 * rb + (lane >> 3)) * K + k0 + 8 * (lane & 7);
;             f32x4 xa[8]; u32x4 ab[4], bb0[4], bb1[4];
;     ...
;             SG_LOAD(0);
.LBB0_258:
	s_lshl_b32 s67, s16, 5
	v_or_b32_e32 v8, s67, v122
	v_ashrrev_i32_e32 v9, 31, v8
	v_lshlrev_b64 v[8:9], 12, v[8:9]
	v_lshl_add_u64 v[108:109], v[102:103], 0, v[8:9]
	v_add_co_u32_e32 v8, vcc, s84, v108
	global_load_dwordx4 v[34:37], v[108:109], off
	s_nop 0
	v_addc_co_u32_e32 v9, vcc, 0, v109, vcc
	v_add_co_u32_e32 v10, vcc, s39, v108
	v_add_u32_e32 v2, s36, v99
	s_nop 0
	v_addc_co_u32_e32 v11, vcc, 0, v109, vcc
	global_load_dwordx4 v[38:41], v[8:9], off
	global_load_dwordx4 v[42:45], v[10:11], off
	v_add_co_u32_e32 v8, vcc, s38, v108
	v_ashrrev_i32_e32 v3, 31, v2
	s_nop 0
	v_addc_co_u32_e32 v9, vcc, 0, v109, vcc
	v_add_co_u32_e32 v10, vcc, s19, v108
	v_lshlrev_b64 v[2:3], 11, v[2:3]
	s_nop 0
	v_addc_co_u32_e32 v11, vcc, 0, v109, vcc
	global_load_dwordx4 v[46:49], v[8:9], off
	global_load_dwordx4 v[50:53], v[10:11], off
	v_add_co_u32_e32 v8, vcc, s20, v108
	v_add_u32_e32 v6, s17, v99
	s_nop 0
	v_addc_co_u32_e32 v9, vcc, 0, v109, vcc
	v_add_co_u32_e32 v10, vcc, s21, v108
	v_lshl_add_u64 v[4:5], v[100:101], 0, v[2:3]
	s_nop 0
	v_addc_co_u32_e32 v11, vcc, 0, v109, vcc
	global_load_dwordx4 v[54:57], v[8:9], off
	global_load_dwordx4 v[58:61], v[10:11], off
	v_add_co_u32_e32 v8, vcc, s71, v108
	v_ashrrev_i32_e32 v7, 31, v6
	s_nop 0
	v_addc_co_u32_e32 v9, vcc, 0, v109, vcc
	v_lshlrev_b64 v[6:7], 11, v[6:7]
	v_add_co_u32_e32 v10, vcc, s84, v4
	global_load_dwordx4 v[62:65], v[8:9], off
	v_lshl_add_u64 v[8:9], v[100:101], 0, v[6:7]
	v_addc_co_u32_e32 v11, vcc, 0, v5, vcc
	global_load_dwordx4 v[66:69], v[4:5], off
	global_load_dwordx4 v[70:73], v[8:9], off
	global_load_dwordx4 v[74:77], v[10:11], off
	v_add_co_u32_e32 v10, vcc, s84, v8
	v_lshl_add_u64 v[118:119], v[106:107], 0, v[2:3]
	s_nop 0
	v_addc_co_u32_e32 v11, vcc, 0, v9, vcc
	v_add_co_u32_e32 v12, vcc, s39, v4
	v_mov_b32_e32 v2, 0
	s_nop 0
	v_addc_co_u32_e32 v13, vcc, 0, v5, vcc
	global_load_dwordx4 v[78:81], v[10:11], off
	global_load_dwordx4 v[82:85], v[12:13], off
	v_add_co_u32_e32 v10, vcc, s39, v8
	v_lshl_add_u64 v[120:121], v[106:107], 0, v[6:7]
	s_nop 0
	v_addc_co_u32_e32 v11, vcc, 0, v9, vcc
	v_add_co_u32_e32 v4, vcc, 0xc000, v4
	s_mov_b64 s[12:13], 0
	s_nop 0
	v_addc_co_u32_e32 v5, vcc, 0, v5, vcc
	global_load_dwordx4 v[86:89], v[10:11], off
	global_load_dwordx4 v[90:93], v[4:5], off
	v_add_co_u32_e32 v4, vcc, 0xc000, v8
	v_mov_b32_e32 v3, v2
	s_nop 0
	v_addc_co_u32_e32 v5, vcc, 0, v9, vcc
	global_load_dwordx4 v[94:97], v[4:5], off
	v_mov_b32_e32 v4, v2
	v_mov_b32_e32 v5, v2
	v_mov_b32_e32 v6, v2
	v_mov_b32_e32 v7, v2
	v_mov_b32_e32 v8, v2
	v_mov_b32_e32 v9, v2
	v_mov_b32_e32 v10, v2
	v_mov_b32_e32 v11, v2
	v_mov_b32_e32 v12, v2
	v_mov_b32_e32 v13, v2
	v_mov_b32_e32 v14, v2
	v_mov_b32_e32 v15, v2
	v_mov_b32_e32 v16, v2
	v_mov_b32_e32 v17, v2
	v_mov_b32_e32 v18, v2
	v_mov_b32_e32 v19, v2
	v_mov_b32_e32 v20, v2
	v_mov_b32_e32 v21, v2
	v_mov_b32_e32 v22, v2
	v_mov_b32_e32 v23, v2
	v_mov_b32_e32 v24, v2
	v_mov_b32_e32 v25, v2
	v_mov_b32_e32 v26, v2
	v_mov_b32_e32 v27, v2
	v_mov_b32_e32 v28, v2
	v_mov_b32_e32 v29, v2
	v_mov_b32_e32 v30, v2
	v_mov_b32_e32 v31, v2
	v_mov_b32_e32 v32, v2
	v_mov_b32_e32 v33, v2
	v_mov_b32_e32 v116, v2
	v_mov_b32_e32 v117, v2
	v_mov_b32_e32 v114, v2
	v_mov_b32_e32 v115, v2
	v_mov_b32_e32 v112, v2
	v_mov_b32_e32 v113, v2
	v_mov_b32_e32 v110, v2
	v_mov_b32_e32 v111, v2
	v_lshl_add_u64 v[182:183], v[108:109], 0, s[12:13]
	v_add_co_u32_e32 v148, vcc, s84, v182
	v_lshl_add_u64 v[224:225], v[118:119], 0, s[28:29]
	s_nop 0
	v_addc_co_u32_e32 v149, vcc, 0, v183, vcc
	v_add_co_u32_e32 v152, vcc, s39, v182
	v_lshl_add_u64 v[228:229], v[120:121], 0, s[28:29]
	s_nop 0
	v_addc_co_u32_e32 v153, vcc, 0, v183, vcc
	v_add_co_u32_e32 v156, vcc, s38, v182
	global_load_dwordx4 v[144:147], v[182:183], off offset:256
	s_nop 0
	global_load_dwordx4 v[148:151], v[148:149], off offset:256
	v_addc_co_u32_e32 v157, vcc, 0, v183, vcc
	v_add_co_u32_e32 v174, vcc, s19, v182
	global_load_dwordx4 v[152:155], v[152:153], off offset:256
	s_nop 0
	global_load_dwordx4 v[156:159], v[156:157], off offset:256
	v_addc_co_u32_e32 v175, vcc, 0, v183, vcc
	v_add_co_u32_e32 v178, vcc, s20, v182
	s_nop 1
	v_addc_co_u32_e32 v179, vcc, 0, v183, vcc
	v_add_co_u32_e32 v184, vcc, s21, v182
	global_load_dwordx4 v[174:177], v[174:175], off offset:256
	s_nop 0
	global_load_dwordx4 v[178:181], v[178:179], off offset:256
	v_addc_co_u32_e32 v185, vcc, 0, v183, vcc
	v_add_co_u32_e32 v186, vcc, s71, v182
	s_nop 1
	v_addc_co_u32_e32 v187, vcc, 0, v183, vcc
	v_add_co_u32_e32 v190, vcc, s22, v224
	global_load_dwordx4 v[182:185], v[184:185], off offset:256
	s_nop 0
	global_load_dwordx4 v[186:189], v[186:187], off offset:256
	v_addc_co_u32_e32 v191, vcc, 0, v225, vcc
	v_add_co_u32_e32 v194, vcc, s22, v228
	global_load_dwordx4 v[190:193], v[190:191], off offset:128
	s_nop 0
	v_addc_co_u32_e32 v195, vcc, 0, v229, vcc
	v_add_co_u32_e32 v208, vcc, s23, v224
	global_load_dwordx4 v[194:197], v[194:195], off offset:128
	s_nop 0
	v_addc_co_u32_e32 v209, vcc, 0, v225, vcc
	v_add_co_u32_e32 v212, vcc, s23, v228
	global_load_dwordx4 v[208:211], v[208:209], off offset:128
	s_nop 0
	v_addc_co_u32_e32 v213, vcc, 0, v229, vcc
	v_add_co_u32_e32 v216, vcc, s85, v224
	global_load_dwordx4 v[212:215], v[212:213], off offset:128
	s_nop 0
	v_addc_co_u32_e32 v217, vcc, 0, v225, vcc
	v_add_co_u32_e32 v220, vcc, s85, v228
	global_load_dwordx4 v[216:219], v[216:217], off offset:128
	s_nop 0
	v_addc_co_u32_e32 v221, vcc, 0, v229, vcc
	v_add_co_u32_e32 v224, vcc, s48, v224
	global_load_dwordx4 v[220:223], v[220:221], off offset:128
	s_nop 0
	v_addc_co_u32_e32 v225, vcc, 0, v225, vcc
	v_add_co_u32_e32 v228, vcc, s48, v228
	global_load_dwordx4 v[224:227], v[224:225], off offset:128
	s_nop 0
	v_addc_co_u32_e32 v229, vcc, 0, v229, vcc
	global_load_dwordx4 v[228:231], v[228:229], off offset:128
; #define LAS __attribute__((address_space(3)))
; __device__ __forceinline__ unsigned cvtpk(float lo, float hi) { f32x2 v = {lo, hi}; bf16x2_t b = __builtin_convertvector(v, bf16x2_t); return __builtin_bit_cast(unsigned, b); }
; #define MFMA32(a, b, c) __builtin_amdgcn_mfma_f32_32x32x16_bf16((a), (b), (c), 0, 0, 0)
;     ...
;             SG_LOAD(0);
;             for (int kb = 0; kb < nb; ++kb) {
;                 __builtin_amdgcn_sched_barrier(0);
;                 if constexpr (AF32) {
; #pragma unroll
;                     for (int i = 0; i < 8; ++i) { const f32x4 x = xa[i]; q8[i] += (x[0] * x[0] + x[1] * x[1]) + (x[2] * x[2] + x[3] * x[3]);
;                         u32x2 w; w.x = cvtpk(x[0], x[1]); w.y = cvtpk(x[2], x[3]); *(LAS u32x2*)(SA + (4 * i + (lane >> 4)) * PITCH + 8 * (lane & 15)) = w; }
;                 } else {
; #pragma unroll
;                     for (int i = 0; i < 4; ++i) *(LAS u32x4*)(SA + (8 * i + (lane >> 3)) * PITCH + 16 * (lane & 7)) = ab[i];
;                 }
; #pragma unroll
;                 for (int i = 0; i < 4; ++i) { *(LAS u32x4*)(SB0 + (8 * i + (lane >> 3)) * PITCH + 16 * (lane & 7)) = bb0[i]; *(LAS u32x4*)(SB1 + (8 * i + (lane >> 3)) * PITCH + 16 * (lane & 7)) = bb1[i]; }
;                 __builtin_amdgcn_sched_barrier(0);
;                 if (kb + 1 < nb) SG_LOAD(kb + 1);
;                 __builtin_amdgcn_sched_barrier(0);
; #pragma unroll
;                 for (int j = 0; j < 4; ++j) {
;                     const bf16x8 af = *(const LAS bf16x8*)(SA + r32 * PITCH + 32 * j + 16 * hi);
;                     const bf16x8 f0 = *(const LAS bf16x8*)(SB0 + r32 * PITCH + 32 * j + 16 * hi), f1 = *(const LAS bf16x8*)(SB1 + r32 * PITCH + 32 * j + 16 * hi);
;                     acc0 = MFMA32(af, f0, acc0); acc1 = MFMA32(af, f1, acc1);
;                 }
.LBB0_259:
	s_waitcnt vmcnt(31)
	v_cvt_pk_bf16_f32 v134, v34, v35
	v_mov_b32_e32 v136, v34
	v_mov_b32_e32 v34, v35
	s_waitcnt vmcnt(30)
	v_mov_b32_e32 v35, v39
	v_mov_b32_e32 v137, v38
	v_pk_mul_f32 v[34:35], v[34:35], v[34:35]
	v_cvt_pk_bf16_f32 v135, v36, v37
	v_pk_fma_f32 v[34:35], v[136:137], v[136:137], v[34:35]
	v_mov_b32_e32 v136, v36
	v_mov_b32_e32 v36, v37
	v_mov_b32_e32 v37, v41
	v_mov_b32_e32 v137, v40
	v_pk_mul_f32 v[36:37], v[36:37], v[36:37]
	v_add_u32_e32 v0, 0x800, v130
	v_pk_fma_f32 v[36:37], v[136:137], v[136:137], v[36:37]
	s_nop 0
	v_pk_add_f32 v[34:35], v[34:35], v[36:37]
	s_waitcnt vmcnt(29)
	v_mov_b32_e32 v36, v42
	v_pk_add_f32 v[110:111], v[110:111], v[34:35]
	v_cvt_pk_bf16_f32 v34, v38, v39
	v_mov_b32_e32 v38, v43
	s_waitcnt vmcnt(28)
	v_mov_b32_e32 v39, v47
	v_cvt_pk_bf16_f32 v35, v40, v41
	v_mov_b32_e32 v37, v46
	v_pk_mul_f32 v[38:39], v[38:39], v[38:39]
	v_mov_b32_e32 v40, v45
	v_mov_b32_e32 v41, v49
	v_pk_fma_f32 v[36:37], v[36:37], v[36:37], v[38:39]
	v_mov_b32_e32 v38, v44
	v_mov_b32_e32 v39, v48
	v_pk_mul_f32 v[40:41], v[40:41], v[40:41]
	ds_write2_b64 v130, v[134:135], v[34:35] offset1:72
	v_pk_fma_f32 v[38:39], v[38:39], v[38:39], v[40:41]
	v_cvt_pk_bf16_f32 v34, v42, v43
	v_pk_add_f32 v[36:37], v[36:37], v[38:39]
	v_cvt_pk_bf16_f32 v35, v44, v45
	v_pk_add_f32 v[112:113], v[112:113], v[36:37]
	v_cvt_pk_bf16_f32 v36, v46, v47
	v_cvt_pk_bf16_f32 v37, v48, v49
	s_waitcnt vmcnt(27)
	v_mov_b32_e32 v38, v51
	s_waitcnt vmcnt(26)
	v_mov_b32_e32 v39, v55
	ds_write2_b64 v130, v[34:35], v[36:37] offset0:144 offset1:216
	v_mov_b32_e32 v36, v50
	v_mov_b32_e32 v37, v54
	v_pk_mul_f32 v[38:39], v[38:39], v[38:39]
	v_mov_b32_e32 v40, v53
	v_mov_b32_e32 v41, v57
	v_pk_fma_f32 v[36:37], v[36:37], v[36:37], v[38:39]
	v_mov_b32_e32 v38, v52
	v_mov_b32_e32 v39, v56
	v_pk_mul_f32 v[40:41], v[40:41], v[40:41]
	v_cvt_pk_bf16_f32 v34, v50, v51
	v_pk_fma_f32 v[38:39], v[38:39], v[38:39], v[40:41]
	v_cvt_pk_bf16_f32 v35, v52, v53
	v_pk_add_f32 v[36:37], v[36:37], v[38:39]
	s_waitcnt vmcnt(25)
	v_mov_b32_e32 v38, v59
	v_pk_add_f32 v[114:115], v[114:115], v[36:37]
	v_cvt_pk_bf16_f32 v36, v54, v55
	v_cvt_pk_bf16_f32 v37, v56, v57
	s_waitcnt vmcnt(24)
	v_mov_b32_e32 v39, v63
	ds_write2_b64 v0, v[34:35], v[36:37] offset0:32 offset1:104
	v_mov_b32_e32 v36, v58
	v_mov_b32_e32 v37, v62
	v_pk_mul_f32 v[38:39], v[38:39], v[38:39]
	v_mov_b32_e32 v40, v61
	v_mov_b32_e32 v41, v65
	v_pk_fma_f32 v[36:37], v[36:37], v[36:37], v[38:39]
	v_mov_b32_e32 v38, v60
	v_mov_b32_e32 v39, v64
	v_pk_mul_f32 v[40:41], v[40:41], v[40:41]
	v_cvt_pk_bf16_f32 v34, v58, v59
	v_pk_fma_f32 v[38:39], v[38:39], v[38:39], v[40:41]
	v_cvt_pk_bf16_f32 v35, v60, v61
	v_pk_add_f32 v[36:37], v[36:37], v[38:39]
	s_nop 0
	v_pk_add_f32 v[116:117], v[116:117], v[36:37]
	v_cvt_pk_bf16_f32 v36, v62, v63
	v_cvt_pk_bf16_f32 v37, v64, v65
	ds_write2_b64 v0, v[34:35], v[36:37] offset0:176 offset1:248
	s_waitcnt vmcnt(23)
	ds_write_b128 v131, v[66:69] offset:4608
	s_waitcnt vmcnt(22)
	ds_write_b128 v131, v[70:73] offset:9216
	s_waitcnt vmcnt(21)
	ds_write_b128 v131, v[74:77] offset:5760
	s_waitcnt vmcnt(20)
	ds_write_b128 v131, v[78:81] offset:10368
	s_waitcnt vmcnt(19)
	ds_write_b128 v131, v[82:85] offset:6912
	s_waitcnt vmcnt(18)
	ds_write_b128 v131, v[86:89] offset:11520
	s_waitcnt vmcnt(17)
	ds_write_b128 v131, v[90:93] offset:8064
	s_waitcnt vmcnt(16)
	ds_write_b128 v131, v[94:97] offset:12672
	v_lshl_add_u64 v[58:59], v[108:109], 0, s[12:13]
	v_add_co_u32_e32 v38, vcc, s84, v58
	v_lshl_add_u64 v[90:91], v[118:119], 0, s[28:29]
	s_nop 0
	v_addc_co_u32_e32 v39, vcc, 0, v59, vcc
	v_add_co_u32_e32 v42, vcc, s39, v58
	v_lshl_add_u64 v[94:95], v[120:121], 0, s[28:29]
	s_nop 0
	v_addc_co_u32_e32 v43, vcc, 0, v59, vcc
	v_add_co_u32_e32 v46, vcc, s38, v58
	global_load_dwordx4 v[34:37], v[58:59], off offset:512
	s_nop 0
	global_load_dwordx4 v[38:41], v[38:39], off offset:512
	v_addc_co_u32_e32 v47, vcc, 0, v59, vcc
	v_add_co_u32_e32 v50, vcc, s19, v58
	global_load_dwordx4 v[42:45], v[42:43], off offset:512
	s_nop 0
	global_load_dwordx4 v[46:49], v[46:47], off offset:512
	v_addc_co_u32_e32 v51, vcc, 0, v59, vcc
	v_add_co_u32_e32 v54, vcc, s20, v58
	s_nop 1
	v_addc_co_u32_e32 v55, vcc, 0, v59, vcc
	v_add_co_u32_e32 v60, vcc, s21, v58
	global_load_dwordx4 v[50:53], v[50:51], off offset:512
	s_nop 0
	global_load_dwordx4 v[54:57], v[54:55], off offset:512
	v_addc_co_u32_e32 v61, vcc, 0, v59, vcc
	v_add_co_u32_e32 v62, vcc, s71, v58
	s_nop 1
	v_addc_co_u32_e32 v63, vcc, 0, v59, vcc
	v_add_co_u32_e32 v66, vcc, s22, v90
	global_load_dwordx4 v[58:61], v[60:61], off offset:512
	s_nop 0
	global_load_dwordx4 v[62:65], v[62:63], off offset:512
	v_addc_co_u32_e32 v67, vcc, 0, v91, vcc
	v_add_co_u32_e32 v70, vcc, s22, v94
	global_load_dwordx4 v[66:69], v[66:67], off offset:256
	s_nop 0
	v_addc_co_u32_e32 v71, vcc, 0, v95, vcc
	v_add_co_u32_e32 v74, vcc, s23, v90
	global_load_dwordx4 v[70:73], v[70:71], off offset:256
	s_nop 0
	v_addc_co_u32_e32 v75, vcc, 0, v91, vcc
	v_add_co_u32_e32 v78, vcc, s23, v94
	global_load_dwordx4 v[74:77], v[74:75], off offset:256
	s_nop 0
	v_addc_co_u32_e32 v79, vcc, 0, v95, vcc
	v_add_co_u32_e32 v82, vcc, s85, v90
	global_load_dwordx4 v[78:81], v[78:79], off offset:256
	s_nop 0
	v_addc_co_u32_e32 v83, vcc, 0, v91, vcc
	v_add_co_u32_e32 v86, vcc, s85, v94
	global_load_dwordx4 v[82:85], v[82:83], off offset:256
	s_nop 0
	v_addc_co_u32_e32 v87, vcc, 0, v95, vcc
	v_add_co_u32_e32 v90, vcc, s48, v90
	global_load_dwordx4 v[86:89], v[86:87], off offset:256
	s_nop 0
	v_addc_co_u32_e32 v91, vcc, 0, v91, vcc
	v_add_co_u32_e32 v94, vcc, s48, v94
	global_load_dwordx4 v[90:93], v[90:91], off offset:256
	s_nop 0
	v_addc_co_u32_e32 v95, vcc, 0, v95, vcc
	global_load_dwordx4 v[94:97], v[94:95], off offset:256
	ds_read_b128 v[134:137], v132
	ds_read_b128 v[138:141], v132 offset:4608
	s_waitcnt lgkmcnt(0)
; #define LAS __attribute__((address_space(3)))
; __device__ __forceinline__ unsigned cvtpk(float lo, float hi) { f32x2 v = {lo, hi}; bf16x2_t b = __builtin_convertvector(v, bf16x2_t); return __builtin_bit_cast(unsigned, b); }
; #define MFMA32(a, b, c) __builtin_amdgcn_mfma_f32_32x32x16_bf16((a), (b), (c), 0, 0, 0)
;     ...
;             for (int kb = 0; kb < nb; ++kb) {
;                 __builtin_amdgcn_sched_barrier(0);
;                 if constexpr (AF32) {
; #pragma unroll
;                     for (int i = 0; i < 8; ++i) { const f32x4 x = xa[i]; q8[i] += (x[0] * x[0] + x[1] * x[1]) + (x[2] * x[2] + x[3] * x[3]);
;                         u32x2 w; w.x = cvtpk(x[0], x[1]); w.y = cvtpk(x[2], x[3]); *(LAS u32x2*)(SA + (4 * i + (lane >> 4)) * PITCH + 8 * (lane & 15)) = w; }
;                 } else {
; #pragma unroll
;                     for (int i = 0; i < 4; ++i) *(LAS u32x4*)(SA + (8 * i + (lane >> 3)) * PITCH + 16 * (lane & 7)) = ab[i];
;                 }
; #pragma unroll
;                 for (int i = 0; i < 4; ++i) { *(LAS u32x4*)(SB0 + (8 * i + (lane >> 3)) * PITCH + 16 * (lane & 7)) = bb0[i]; *(LAS u32x4*)(SB1 + (8 * i + (lane >> 3)) * PITCH + 16 * (lane & 7)) = bb1[i]; }
;                 __builtin_amdgcn_sched_barrier(0);
;                 if (kb + 1 < nb) SG_LOAD(kb + 1);
;                 __builtin_amdgcn_sched_barrier(0);
; #pragma unroll
;                 for (int j = 0; j < 4; ++j) {
;                     const bf16x8 af = *(const LAS bf16x8*)(SA + r32 * PITCH + 32 * j + 16 * hi);
;                     const bf16x8 f0 = *(const LAS bf16x8*)(SB0 + r32 * PITCH + 32 * j + 16 * hi), f1 = *(const LAS bf16x8*)(SB1 + r32 * PITCH + 32 * j + 16 * hi);
;                     acc0 = MFMA32(af, f0, acc0); acc1 = MFMA32(af, f1, acc1);
;                 }
	v_mfma_f32_32x32x16_bf16 v[2:17], v[134:137], v[138:141], v[2:17]
	ds_read_b128 v[138:141], v132 offset:9216
	s_waitcnt lgkmcnt(0)
	v_mfma_f32_32x32x16_bf16 v[18:33], v[134:137], v[138:141], v[18:33]
	ds_read_b128 v[134:137], v132 offset:32
	ds_read_b128 v[138:141], v132 offset:4640
	s_waitcnt lgkmcnt(0)
	v_mfma_f32_32x32x16_bf16 v[2:17], v[134:137], v[138:141], v[2:17]
	ds_read_b128 v[138:141], v132 offset:9248
	s_waitcnt lgkmcnt(0)
	v_mfma_f32_32x32x16_bf16 v[18:33], v[134:137], v[138:141], v[18:33]
	ds_read_b128 v[134:137], v132 offset:64
	ds_read_b128 v[138:141], v132 offset:4672
	s_waitcnt lgkmcnt(0)
	v_mfma_f32_32x32x16_bf16 v[2:17], v[134:137], v[138:141], v[2:17]
	ds_read_b128 v[138:141], v132 offset:9280
	s_waitcnt lgkmcnt(0)
	v_mfma_f32_32x32x16_bf16 v[18:33], v[134:137], v[138:141], v[18:33]
	ds_read_b128 v[134:137], v132 offset:96
	ds_read_b128 v[138:141], v132 offset:4704
	s_waitcnt lgkmcnt(0)
	v_mfma_f32_32x32x16_bf16 v[2:17], v[134:137], v[138:141], v[2:17]
	ds_read_b128 v[138:141], v132 offset:9312
	s_waitcnt lgkmcnt(0)
	v_mfma_f32_32x32x16_bf16 v[18:33], v[134:137], v[138:141], v[18:33]
	s_waitcnt vmcnt(31)
	v_cvt_pk_bf16_f32 v134, v144, v145
	v_mov_b32_e32 v136, v144
	v_mov_b32_e32 v144, v145
	s_waitcnt vmcnt(30)
	v_mov_b32_e32 v145, v149
	v_mov_b32_e32 v137, v148
	v_pk_mul_f32 v[144:145], v[144:145], v[144:145]
	v_cvt_pk_bf16_f32 v135, v146, v147
	v_pk_fma_f32 v[144:145], v[136:137], v[136:137], v[144:145]
	v_mov_b32_e32 v136, v146
	v_mov_b32_e32 v146, v147
	v_mov_b32_e32 v147, v151
	v_mov_b32_e32 v137, v150
	v_pk_mul_f32 v[146:147], v[146:147], v[146:147]
	v_add_u32_e32 v0, 0x800, v130
	v_pk_fma_f32 v[146:147], v[136:137], v[136:137], v[146:147]
	s_nop 0
	v_pk_add_f32 v[144:145], v[144:145], v[146:147]
	s_waitcnt vmcnt(29)
	v_mov_b32_e32 v146, v152
	v_pk_add_f32 v[110:111], v[110:111], v[144:145]
	v_cvt_pk_bf16_f32 v144, v148, v149
	v_mov_b32_e32 v148, v153
	s_waitcnt vmcnt(28)
	v_mov_b32_e32 v149, v157
	v_cvt_pk_bf16_f32 v145, v150, v151
	v_mov_b32_e32 v147, v156
	v_pk_mul_f32 v[148:149], v[148:149], v[148:149]
	v_mov_b32_e32 v150, v155
	v_mov_b32_e32 v151, v159
	v_pk_fma_f32 v[146:147], v[146:147], v[146:147], v[148:149]
	v_mov_b32_e32 v148, v154
	v_mov_b32_e32 v149, v158
	v_pk_mul_f32 v[150:151], v[150:151], v[150:151]
	ds_write2_b64 v130, v[134:135], v[144:145] offset1:72
	v_pk_fma_f32 v[148:149], v[148:149], v[148:149], v[150:151]
	v_cvt_pk_bf16_f32 v144, v152, v153
	v_pk_add_f32 v[146:147], v[146:147], v[148:149]
	v_cvt_pk_bf16_f32 v145, v154, v155
	v_pk_add_f32 v[112:113], v[112:113], v[146:147]
	v_cvt_pk_bf16_f32 v146, v156, v157
	v_cvt_pk_bf16_f32 v147, v158, v159
	s_waitcnt vmcnt(27)
	v_mov_b32_e32 v148, v175
	s_waitcnt vmcnt(26)
	v_mov_b32_e32 v149, v179
	ds_write2_b64 v130, v[144:145], v[146:147] offset0:144 offset1:216
	v_mov_b32_e32 v146, v174
	v_mov_b32_e32 v147, v178
	v_pk_mul_f32 v[148:149], v[148:149], v[148:149]
	v_mov_b32_e32 v150, v177
	v_mov_b32_e32 v151, v181
	v_pk_fma_f32 v[146:147], v[146:147], v[146:147], v[148:149]
	v_mov_b32_e32 v148, v176
	v_mov_b32_e32 v149, v180
	v_pk_mul_f32 v[150:151], v[150:151], v[150:151]
	v_cvt_pk_bf16_f32 v144, v174, v175
	v_pk_fma_f32 v[148:149], v[148:149], v[148:149], v[150:151]
	v_cvt_pk_bf16_f32 v145, v176, v177
	v_pk_add_f32 v[146:147], v[146:147], v[148:149]
	s_waitcnt vmcnt(25)
	v_mov_b32_e32 v148, v183
	v_pk_add_f32 v[114:115], v[114:115], v[146:147]
	v_cvt_pk_bf16_f32 v146, v178, v179
	v_cvt_pk_bf16_f32 v147, v180, v181
	s_waitcnt vmcnt(24)
	v_mov_b32_e32 v149, v187
	ds_write2_b64 v0, v[144:145], v[146:147] offset0:32 offset1:104
	v_mov_b32_e32 v146, v182
	v_mov_b32_e32 v147, v186
	v_pk_mul_f32 v[148:149], v[148:149], v[148:149]
	v_mov_b32_e32 v150, v185
	v_mov_b32_e32 v151, v189
	v_pk_fma_f32 v[146:147], v[146:147], v[146:147], v[148:149]
	v_mov_b32_e32 v148, v184
	v_mov_b32_e32 v149, v188
	v_pk_mul_f32 v[150:151], v[150:151], v[150:151]
	v_cvt_pk_bf16_f32 v144, v182, v183
	v_pk_fma_f32 v[148:149], v[148:149], v[148:149], v[150:151]
	v_cvt_pk_bf16_f32 v145, v184, v185
	v_pk_add_f32 v[146:147], v[146:147], v[148:149]
	s_nop 0
	v_pk_add_f32 v[116:117], v[116:117], v[146:147]
	v_cvt_pk_bf16_f32 v146, v186, v187
	v_cvt_pk_bf16_f32 v147, v188, v189
	ds_write2_b64 v0, v[144:145], v[146:147] offset0:176 offset1:248
	s_waitcnt vmcnt(23)
	ds_write_b128 v131, v[190:193] offset:4608
	s_waitcnt vmcnt(22)
	ds_write_b128 v131, v[194:197] offset:9216
	s_waitcnt vmcnt(21)
	ds_write_b128 v131, v[208:211] offset:5760
	s_waitcnt vmcnt(20)
	ds_write_b128 v131, v[212:215] offset:10368
	s_waitcnt vmcnt(19)
	ds_write_b128 v131, v[216:219] offset:6912
	s_waitcnt vmcnt(18)
	ds_write_b128 v131, v[220:223] offset:11520
	s_waitcnt vmcnt(17)
	ds_write_b128 v131, v[224:227] offset:8064
	s_waitcnt vmcnt(16)
; #define LAS __attribute__((address_space(3)))
; __device__ __forceinline__ unsigned cvtpk(float lo, float hi) { f32x2 v = {lo, hi}; bf16x2_t b = __builtin_convertvector(v, bf16x2_t); return __builtin_bit_cast(unsigned, b); }
; #define MFMA32(a, b, c) __builtin_amdgcn_mfma_f32_32x32x16_bf16((a), (b), (c), 0, 0, 0)
;     ...
;             SG_LOAD(0);
;             for (int kb = 0; kb < nb; ++kb) {
;                 __builtin_amdgcn_sched_barrier(0);
;                 if constexpr (AF32) {
; #pragma unroll
;                     for (int i = 0; i < 8; ++i) { const f32x4 x = xa[i]; q8[i] += (x[0] * x[0] + x[1] * x[1]) + (x[2] * x[2] + x[3] * x[3]);
;                         u32x2 w; w.x = cvtpk(x[0], x[1]); w.y = cvtpk(x[2], x[3]); *(LAS u32x2*)(SA + (4 * i + (lane >> 4)) * PITCH + 8 * (lane & 15)) = w; }
;                 } else {
; #pragma unroll
;                     for (int i = 0; i < 4; ++i) *(LAS u32x4*)(SA + (8 * i + (lane >> 3)) * PITCH + 16 * (lane & 7)) = ab[i];
;                 }
; #pragma unroll
;                 for (int i = 0; i < 4; ++i) { *(LAS u32x4*)(SB0 + (8 * i + (lane >> 3)) * PITCH + 16 * (lane & 7)) = bb0[i]; *(LAS u32x4*)(SB1 + (8 * i + (lane >> 3)) * PITCH + 16 * (lane & 7)) = bb1[i]; }
;                 __builtin_amdgcn_sched_barrier(0);
;                 if (kb + 1 < nb) SG_LOAD(kb + 1);
;                 __builtin_amdgcn_sched_barrier(0);
; #pragma unroll
;                 for (int j = 0; j < 4; ++j) {
;                     const bf16x8 af = *(const LAS bf16x8*)(SA + r32 * PITCH + 32 * j + 16 * hi);
;                     const bf16x8 f0 = *(const LAS bf16x8*)(SB0 + r32 * PITCH + 32 * j + 16 * hi), f1 = *(const LAS bf16x8*)(SB1 + r32 * PITCH + 32 * j + 16 * hi);
;                     acc0 = MFMA32(af, f0, acc0); acc1 = MFMA32(af, f1, acc1);
;                 }
	ds_write_b128 v131, v[228:231] offset:12672
	v_lshl_add_u64 v[182:183], v[108:109], 0, s[12:13]
	v_add_co_u32_e32 v148, vcc, s84, v182
	v_lshl_add_u64 v[224:225], v[118:119], 0, s[28:29]
	s_nop 0
	v_addc_co_u32_e32 v149, vcc, 0, v183, vcc
	v_add_co_u32_e32 v152, vcc, s39, v182
	v_lshl_add_u64 v[228:229], v[120:121], 0, s[28:29]
	s_nop 0
	v_addc_co_u32_e32 v153, vcc, 0, v183, vcc
	v_add_co_u32_e32 v156, vcc, s38, v182
	global_load_dwordx4 v[144:147], v[182:183], off offset:768
	s_nop 0
	global_load_dwordx4 v[148:151], v[148:149], off offset:768
	v_addc_co_u32_e32 v157, vcc, 0, v183, vcc
	v_add_co_u32_e32 v174, vcc, s19, v182
	global_load_dwordx4 v[152:155], v[152:153], off offset:768
	s_nop 0
	global_load_dwordx4 v[156:159], v[156:157], off offset:768
	v_addc_co_u32_e32 v175, vcc, 0, v183, vcc
	v_add_co_u32_e32 v178, vcc, s20, v182
	s_nop 1
	v_addc_co_u32_e32 v179, vcc, 0, v183, vcc
	v_add_co_u32_e32 v184, vcc, s21, v182
	global_load_dwordx4 v[174:177], v[174:175], off offset:768
	s_nop 0
	global_load_dwordx4 v[178:181], v[178:179], off offset:768
	v_addc_co_u32_e32 v185, vcc, 0, v183, vcc
	v_add_co_u32_e32 v186, vcc, s71, v182
	s_nop 1
	v_addc_co_u32_e32 v187, vcc, 0, v183, vcc
	v_add_co_u32_e32 v190, vcc, s22, v224
	global_load_dwordx4 v[182:185], v[184:185], off offset:768
	s_nop 0
	global_load_dwordx4 v[186:189], v[186:187], off offset:768
	v_addc_co_u32_e32 v191, vcc, 0, v225, vcc
	v_add_co_u32_e32 v194, vcc, s22, v228
	global_load_dwordx4 v[190:193], v[190:191], off offset:384
	s_nop 0
	v_addc_co_u32_e32 v195, vcc, 0, v229, vcc
	v_add_co_u32_e32 v208, vcc, s23, v224
	global_load_dwordx4 v[194:197], v[194:195], off offset:384
	s_nop 0
	v_addc_co_u32_e32 v209, vcc, 0, v225, vcc
	v_add_co_u32_e32 v212, vcc, s23, v228
	global_load_dwordx4 v[208:211], v[208:209], off offset:384
	s_nop 0
	v_addc_co_u32_e32 v213, vcc, 0, v229, vcc
	v_add_co_u32_e32 v216, vcc, s85, v224
	global_load_dwordx4 v[212:215], v[212:213], off offset:384
	s_nop 0
	v_addc_co_u32_e32 v217, vcc, 0, v225, vcc
	v_add_co_u32_e32 v220, vcc, s85, v228
	global_load_dwordx4 v[216:219], v[216:217], off offset:384
	s_nop 0
	v_addc_co_u32_e32 v221, vcc, 0, v229, vcc
	v_add_co_u32_e32 v224, vcc, s48, v224
	global_load_dwordx4 v[220:223], v[220:221], off offset:384
	s_nop 0
	v_addc_co_u32_e32 v225, vcc, 0, v225, vcc
	v_add_co_u32_e32 v228, vcc, s48, v228
	global_load_dwordx4 v[224:227], v[224:225], off offset:384
	s_nop 0
	v_addc_co_u32_e32 v229, vcc, 0, v229, vcc
	global_load_dwordx4 v[228:231], v[228:229], off offset:384
	ds_read_b128 v[134:137], v132
	ds_read_b128 v[138:141], v132 offset:4608
	s_add_u32 s12, s12, 0x200
	s_addc_u32 s13, s13, 0
	v_lshl_add_u64 v[118:119], v[118:119], 0, s[0:1]
	v_lshl_add_u64 v[120:121], v[120:121], 0, s[0:1]
	v_lshl_add_u64 v[118:119], v[118:119], 0, s[0:1]
	v_lshl_add_u64 v[120:121], v[120:121], 0, s[0:1]
	s_cmpk_eq_i32 s12, 0x600
	s_waitcnt lgkmcnt(0)
	v_mfma_f32_32x32x16_bf16 v[2:17], v[134:137], v[138:141], v[2:17]
	ds_read_b128 v[138:141], v132 offset:9216
	s_waitcnt lgkmcnt(0)
	v_mfma_f32_32x32x16_bf16 v[18:33], v[134:137], v[138:141], v[18:33]
	ds_read_b128 v[134:137], v132 offset:32
	ds_read_b128 v[138:141], v132 offset:4640
	s_waitcnt lgkmcnt(0)
	v_mfma_f32_32x32x16_bf16 v[2:17], v[134:137], v[138:141], v[2:17]
	ds_read_b128 v[138:141], v132 offset:9248
	s_waitcnt lgkmcnt(0)
	v_mfma_f32_32x32x16_bf16 v[18:33], v[134:137], v[138:141], v[18:33]
	ds_read_b128 v[134:137], v132 offset:64
	ds_read_b128 v[138:141], v132 offset:4672
	s_waitcnt lgkmcnt(0)
	v_mfma_f32_32x32x16_bf16 v[2:17], v[134:137], v[138:141], v[2:17]
	ds_read_b128 v[138:141], v132 offset:9280
	s_waitcnt lgkmcnt(0)
	v_mfma_f32_32x32x16_bf16 v[18:33], v[134:137], v[138:141], v[18:33]
	ds_read_b128 v[134:137], v132 offset:96
	ds_read_b128 v[138:141], v132 offset:4704
	s_waitcnt lgkmcnt(0)
	v_mfma_f32_32x32x16_bf16 v[2:17], v[134:137], v[138:141], v[2:17]
	ds_read_b128 v[138:141], v132 offset:9312
	s_waitcnt lgkmcnt(0)
	v_mfma_f32_32x32x16_bf16 v[18:33], v[134:137], v[138:141], v[18:33]
	s_cbranch_scc0 .LBB0_259
	s_waitcnt vmcnt(31)
	v_cvt_pk_bf16_f32 v134, v34, v35
	v_mov_b32_e32 v136, v34
	v_mov_b32_e32 v34, v35
	s_waitcnt vmcnt(30)
	v_mov_b32_e32 v35, v39
	v_mov_b32_e32 v137, v38
	v_pk_mul_f32 v[34:35], v[34:35], v[34:35]
	v_cvt_pk_bf16_f32 v135, v36, v37
	v_pk_fma_f32 v[34:35], v[136:137], v[136:137], v[34:35]
	v_mov_b32_e32 v136, v36
	v_mov_b32_e32 v36, v37
	v_mov_b32_e32 v37, v41
	v_mov_b32_e32 v137, v40
	v_pk_mul_f32 v[36:37], v[36:37], v[36:37]
	v_add_u32_e32 v0, 0x800, v130
	v_pk_fma_f32 v[36:37], v[136:137], v[136:137], v[36:37]
	s_nop 0
	v_pk_add_f32 v[34:35], v[34:35], v[36:37]
	s_waitcnt vmcnt(29)
	v_mov_b32_e32 v36, v42
	v_pk_add_f32 v[110:111], v[110:111], v[34:35]
	v_cvt_pk_bf16_f32 v34, v38, v39
	v_mov_b32_e32 v38, v43
	s_waitcnt vmcnt(28)
	v_mov_b32_e32 v39, v47
	v_cvt_pk_bf16_f32 v35, v40, v41
	v_mov_b32_e32 v37, v46
	v_pk_mul_f32 v[38:39], v[38:39], v[38:39]
	v_mov_b32_e32 v40, v45
	v_mov_b32_e32 v41, v49
	v_pk_fma_f32 v[36:37], v[36:37], v[36:37], v[38:39]
	v_mov_b32_e32 v38, v44
	v_mov_b32_e32 v39, v48
	v_pk_mul_f32 v[40:41], v[40:41], v[40:41]
	ds_write2_b64 v130, v[134:135], v[34:35] offset1:72
	v_pk_fma_f32 v[38:39], v[38:39], v[38:39], v[40:41]
	v_cvt_pk_bf16_f32 v34, v42, v43
	v_pk_add_f32 v[36:37], v[36:37], v[38:39]
	v_cvt_pk_bf16_f32 v35, v44, v45
	v_pk_add_f32 v[112:113], v[112:113], v[36:37]
	v_cvt_pk_bf16_f32 v36, v46, v47
	v_cvt_pk_bf16_f32 v37, v48, v49
	s_waitcnt vmcnt(27)
	v_mov_b32_e32 v38, v51
	s_waitcnt vmcnt(26)
; #define LAS __attribute__((address_space(3)))
; __device__ __forceinline__ unsigned cvtpk(float lo, float hi) { f32x2 v = {lo, hi}; bf16x2_t b = __builtin_convertvector(v, bf16x2_t); return __builtin_bit_cast(unsigned, b); }
; #define MFMA32(a, b, c) __builtin_amdgcn_mfma_f32_32x32x16_bf16((a), (b), (c), 0, 0, 0)
;     ...
;             for (int kb = 0; kb < nb; ++kb) {
;                 __builtin_amdgcn_sched_barrier(0);
;                 if constexpr (AF32) {
; #pragma unroll
;                     for (int i = 0; i < 8; ++i) { const f32x4 x = xa[i]; q8[i] += (x[0] * x[0] + x[1] * x[1]) + (x[2] * x[2] + x[3] * x[3]);
;                         u32x2 w; w.x = cvtpk(x[0], x[1]); w.y = cvtpk(x[2], x[3]); *(LAS u32x2*)(SA + (4 * i + (lane >> 4)) * PITCH + 8 * (lane & 15)) = w; }
;                 } else {
; #pragma unroll
;                     for (int i = 0; i < 4; ++i) *(LAS u32x4*)(SA + (8 * i + (lane >> 3)) * PITCH + 16 * (lane & 7)) = ab[i];
;                 }
; #pragma unroll
;                 for (int i = 0; i < 4; ++i) { *(LAS u32x4*)(SB0 + (8 * i + (lane >> 3)) * PITCH + 16 * (lane & 7)) = bb0[i]; *(LAS u32x4*)(SB1 + (8 * i + (lane >> 3)) * PITCH + 16 * (lane & 7)) = bb1[i]; }
;                 __builtin_amdgcn_sched_barrier(0);
;                 if (kb + 1 < nb) SG_LOAD(kb + 1);
;                 __builtin_amdgcn_sched_barrier(0);
; #pragma unroll
;                 for (int j = 0; j < 4; ++j) {
;                     const bf16x8 af = *(const LAS bf16x8*)(SA + r32 * PITCH + 32 * j + 16 * hi);
;                     const bf16x8 f0 = *(const LAS bf16x8*)(SB0 + r32 * PITCH + 32 * j + 16 * hi), f1 = *(const LAS bf16x8*)(SB1 + r32 * PITCH + 32 * j + 16 * hi);
;                     acc0 = MFMA32(af, f0, acc0); acc1 = MFMA32(af, f1, acc1);
;                 }
	v_mov_b32_e32 v39, v55
	ds_write2_b64 v130, v[34:35], v[36:37] offset0:144 offset1:216
	v_mov_b32_e32 v36, v50
	v_mov_b32_e32 v37, v54
	v_pk_mul_f32 v[38:39], v[38:39], v[38:39]
	v_mov_b32_e32 v40, v53
	v_mov_b32_e32 v41, v57
	v_pk_fma_f32 v[36:37], v[36:37], v[36:37], v[38:39]
	v_mov_b32_e32 v38, v52
	v_mov_b32_e32 v39, v56
	v_pk_mul_f32 v[40:41], v[40:41], v[40:41]
	v_cvt_pk_bf16_f32 v34, v50, v51
	v_pk_fma_f32 v[38:39], v[38:39], v[38:39], v[40:41]
	v_cvt_pk_bf16_f32 v35, v52, v53
	v_pk_add_f32 v[36:37], v[36:37], v[38:39]
	s_waitcnt vmcnt(25)
	v_mov_b32_e32 v38, v59
	v_pk_add_f32 v[114:115], v[114:115], v[36:37]
	v_cvt_pk_bf16_f32 v36, v54, v55
	v_cvt_pk_bf16_f32 v37, v56, v57
	s_waitcnt vmcnt(24)
	v_mov_b32_e32 v39, v63
	ds_write2_b64 v0, v[34:35], v[36:37] offset0:32 offset1:104
	v_mov_b32_e32 v36, v58
	v_mov_b32_e32 v37, v62
	v_pk_mul_f32 v[38:39], v[38:39], v[38:39]
	v_mov_b32_e32 v40, v61
	v_mov_b32_e32 v41, v65
	v_pk_fma_f32 v[36:37], v[36:37], v[36:37], v[38:39]
	v_mov_b32_e32 v38, v60
	v_mov_b32_e32 v39, v64
	v_pk_mul_f32 v[40:41], v[40:41], v[40:41]
	v_cvt_pk_bf16_f32 v34, v58, v59
	v_pk_fma_f32 v[38:39], v[38:39], v[38:39], v[40:41]
	v_cvt_pk_bf16_f32 v35, v60, v61
	v_pk_add_f32 v[36:37], v[36:37], v[38:39]
	s_nop 0
	v_pk_add_f32 v[116:117], v[116:117], v[36:37]
	v_cvt_pk_bf16_f32 v36, v62, v63
	v_cvt_pk_bf16_f32 v37, v64, v65
	ds_write2_b64 v0, v[34:35], v[36:37] offset0:176 offset1:248
	s_waitcnt vmcnt(23)
	ds_write_b128 v131, v[66:69] offset:4608
	s_waitcnt vmcnt(22)
	ds_write_b128 v131, v[70:73] offset:9216
	s_waitcnt vmcnt(21)
	ds_write_b128 v131, v[74:77] offset:5760
	s_waitcnt vmcnt(20)
	ds_write_b128 v131, v[78:81] offset:10368
	s_waitcnt vmcnt(19)
	ds_write_b128 v131, v[82:85] offset:6912
	s_waitcnt vmcnt(18)
	ds_write_b128 v131, v[86:89] offset:11520
	s_waitcnt vmcnt(17)
	ds_write_b128 v131, v[90:93] offset:8064
	s_waitcnt vmcnt(16)
	ds_write_b128 v131, v[94:97] offset:12672
	ds_read_b128 v[134:137], v132
	ds_read_b128 v[138:141], v132 offset:4608
	s_waitcnt lgkmcnt(0)
	v_mfma_f32_32x32x16_bf16 v[2:17], v[134:137], v[138:141], v[2:17]
	ds_read_b128 v[138:141], v132 offset:9216
	s_waitcnt lgkmcnt(0)
	v_mfma_f32_32x32x16_bf16 v[18:33], v[134:137], v[138:141], v[18:33]
	ds_read_b128 v[134:137], v132 offset:32
	ds_read_b128 v[138:141], v132 offset:4640
	s_waitcnt lgkmcnt(0)
	v_mfma_f32_32x32x16_bf16 v[2:17], v[134:137], v[138:141], v[2:17]
	ds_read_b128 v[138:141], v132 offset:9248
	s_waitcnt lgkmcnt(0)
	v_mfma_f32_32x32x16_bf16 v[18:33], v[134:137], v[138:141], v[18:33]
	ds_read_b128 v[134:137], v132 offset:64
	ds_read_b128 v[138:141], v132 offset:4672
	s_waitcnt lgkmcnt(0)
	v_mfma_f32_32x32x16_bf16 v[2:17], v[134:137], v[138:141], v[2:17]
	ds_read_b128 v[138:141], v132 offset:9280
	s_waitcnt lgkmcnt(0)
	v_mfma_f32_32x32x16_bf16 v[18:33], v[134:137], v[138:141], v[18:33]
	ds_read_b128 v[134:137], v132 offset:96
	ds_read_b128 v[138:141], v132 offset:4704
	s_waitcnt lgkmcnt(0)
	v_mfma_f32_32x32x16_bf16 v[2:17], v[134:137], v[138:141], v[2:17]
	ds_read_b128 v[138:141], v132 offset:9312
	s_waitcnt lgkmcnt(0)
	v_mfma_f32_32x32x16_bf16 v[18:33], v[134:137], v[138:141], v[18:33]
	s_waitcnt vmcnt(15)
	v_cvt_pk_bf16_f32 v108, v144, v145
	v_cvt_pk_bf16_f32 v109, v146, v147
	s_waitcnt vmcnt(14)
	v_cvt_pk_bf16_f32 v118, v148, v149
	v_cvt_pk_bf16_f32 v119, v150, v151
	ds_write2_b64 v130, v[108:109], v[118:119] offset1:72
	s_waitcnt vmcnt(13)
	v_cvt_pk_bf16_f32 v108, v152, v153
	v_cvt_pk_bf16_f32 v109, v154, v155
	s_waitcnt vmcnt(12)
	v_cvt_pk_bf16_f32 v118, v156, v157
	v_cvt_pk_bf16_f32 v119, v158, v159
	ds_write2_b64 v130, v[108:109], v[118:119] offset0:144 offset1:216
	s_waitcnt vmcnt(11)
	v_cvt_pk_bf16_f32 v108, v174, v175
	v_cvt_pk_bf16_f32 v109, v176, v177
	s_waitcnt vmcnt(10)
	v_cvt_pk_bf16_f32 v118, v178, v179
	v_cvt_pk_bf16_f32 v119, v180, v181
	ds_write2_b64 v0, v[108:109], v[118:119] offset0:32 offset1:104
	s_waitcnt vmcnt(9)
	v_cvt_pk_bf16_f32 v108, v182, v183
	v_cvt_pk_bf16_f32 v109, v184, v185
	s_waitcnt vmcnt(8)
	v_cvt_pk_bf16_f32 v118, v186, v187
	v_cvt_pk_bf16_f32 v119, v188, v189
	ds_write2_b64 v0, v[108:109], v[118:119] offset0:176 offset1:248
	s_waitcnt vmcnt(7)
	ds_write_b128 v131, v[190:193] offset:4608
	s_waitcnt vmcnt(6)
	ds_write_b128 v131, v[194:197] offset:9216
	s_waitcnt vmcnt(5)
	ds_write_b128 v131, v[208:211] offset:5760
	s_waitcnt vmcnt(4)
	ds_write_b128 v131, v[212:215] offset:10368
	s_waitcnt vmcnt(3)
	ds_write_b128 v131, v[216:219] offset:6912
	s_waitcnt vmcnt(2)
	ds_write_b128 v131, v[220:223] offset:11520
	s_waitcnt vmcnt(1)
	ds_write_b128 v131, v[224:227] offset:8064
	s_waitcnt vmcnt(0)
; #define LAS __attribute__((address_space(3)))
; __device__ __forceinline__ unsigned cvtpk(float lo, float hi) { f32x2 v = {lo, hi}; bf16x2_t b = __builtin_convertvector(v, bf16x2_t); return __builtin_bit_cast(unsigned, b); }
; __device__ __forceinline__ void lds_barrier() { asm volatile("s_waitcnt lgkmcnt(0)\n\ts_barrier" ::: "memory"); }
; #define MFMA32(a, b, c) __builtin_amdgcn_mfma_f32_32x32x16_bf16((a), (b), (c), 0, 0, 0)
;     ...
;             for (int kb = 0; kb < nb; ++kb) {
;                 __builtin_amdgcn_sched_barrier(0);
;                 if constexpr (AF32) {
; #pragma unroll
;                     for (int i = 0; i < 8; ++i) { const f32x4 x = xa[i]; q8[i] += (x[0] * x[0] + x[1] * x[1]) + (x[2] * x[2] + x[3] * x[3]);
;                         u32x2 w; w.x = cvtpk(x[0], x[1]); w.y = cvtpk(x[2], x[3]); *(LAS u32x2*)(SA + (4 * i + (lane >> 4)) * PITCH + 8 * (lane & 15)) = w; }
;                 } else {
; #pragma unroll
;                     for (int i = 0; i < 4; ++i) *(LAS u32x4*)(SA + (8 * i + (lane >> 3)) * PITCH + 16 * (lane & 7)) = ab[i];
;                 }
; #pragma unroll
;                 for (int i = 0; i < 4; ++i) { *(LAS u32x4*)(SB0 + (8 * i + (lane >> 3)) * PITCH + 16 * (lane & 7)) = bb0[i]; *(LAS u32x4*)(SB1 + (8 * i + (lane >> 3)) * PITCH + 16 * (lane & 7)) = bb1[i]; }
;                 __builtin_amdgcn_sched_barrier(0);
;                 if (kb + 1 < nb) SG_LOAD(kb + 1);
;                 __builtin_amdgcn_sched_barrier(0);
; #pragma unroll
;                 for (int j = 0; j < 4; ++j) {
;                     const bf16x8 af = *(const LAS bf16x8*)(SA + r32 * PITCH + 32 * j + 16 * hi);
;                     const bf16x8 f0 = *(const LAS bf16x8*)(SB0 + r32 * PITCH + 32 * j + 16 * hi), f1 = *(const LAS bf16x8*)(SB1 + r32 * PITCH + 32 * j + 16 * hi);
;                     acc0 = MFMA32(af, f0, acc0); acc1 = MFMA32(af, f1, acc1);
;                 }
;             }
;     ...
;         }
;         lds_barrier();
;         if (ks != 0) {
; #pragma unroll
;             for (int i = 0; i < 16; ++i) { RED[(wave * 32 + i) * 64 + lane] = acc0[i]; RED[(wave * 32 + 16 + i) * 64 + lane] = acc1[i]; }
	ds_write_b128 v131, v[228:231] offset:12672
	v_mov_b32_e32 v191, v186
	v_mov_b32_e32 v186, v183
	v_mov_b32_e32 v190, v182
	v_pk_mul_f32 v[182:183], v[186:187], v[186:187]
	v_mov_b32_e32 v187, v188
	v_mov_b32_e32 v188, v185
	v_mov_b32_e32 v186, v184
	v_pk_mul_f32 v[184:185], v[188:189], v[188:189]
	v_pk_fma_f32 v[182:183], v[190:191], v[190:191], v[182:183]
	v_pk_fma_f32 v[184:185], v[186:187], v[186:187], v[184:185]
	s_nop 0
	v_pk_add_f32 v[182:183], v[182:183], v[184:185]
	v_mov_b32_e32 v185, v178
	v_mov_b32_e32 v178, v175
	v_mov_b32_e32 v184, v174
	v_pk_mul_f32 v[174:175], v[178:179], v[178:179]
	v_mov_b32_e32 v179, v180
	v_mov_b32_e32 v180, v177
	v_mov_b32_e32 v178, v176
	v_pk_mul_f32 v[176:177], v[180:181], v[180:181]
	v_pk_fma_f32 v[174:175], v[184:185], v[184:185], v[174:175]
	v_pk_fma_f32 v[176:177], v[178:179], v[178:179], v[176:177]
	v_pk_add_f32 v[182:183], v[116:117], v[182:183]
	v_pk_add_f32 v[174:175], v[174:175], v[176:177]
	v_mov_b32_e32 v177, v156
	v_mov_b32_e32 v156, v153
	v_mov_b32_e32 v176, v152
	v_pk_mul_f32 v[152:153], v[156:157], v[156:157]
	v_mov_b32_e32 v157, v158
	v_mov_b32_e32 v158, v155
	v_mov_b32_e32 v156, v154
	v_pk_mul_f32 v[154:155], v[158:159], v[158:159]
	v_pk_fma_f32 v[152:153], v[176:177], v[176:177], v[152:153]
	v_pk_fma_f32 v[154:155], v[156:157], v[156:157], v[154:155]
	v_pk_add_f32 v[174:175], v[114:115], v[174:175]
	v_pk_add_f32 v[152:153], v[152:153], v[154:155]
	s_nop 0
	v_pk_add_f32 v[154:155], v[112:113], v[152:153]
	v_mov_b32_e32 v153, v148
	v_mov_b32_e32 v148, v145
	v_mov_b32_e32 v152, v144
	v_pk_mul_f32 v[144:145], v[148:149], v[148:149]
	v_mov_b32_e32 v149, v150
	v_mov_b32_e32 v150, v147
	v_mov_b32_e32 v148, v146
	v_pk_mul_f32 v[146:147], v[150:151], v[150:151]
	v_pk_fma_f32 v[144:145], v[152:153], v[152:153], v[144:145]
	v_pk_fma_f32 v[146:147], v[148:149], v[148:149], v[146:147]
	s_nop 0
	v_pk_add_f32 v[144:145], v[144:145], v[146:147]
	s_nop 0
	v_pk_add_f32 v[150:151], v[110:111], v[144:145]
	ds_read_b128 v[144:147], v132
	ds_read_b128 v[156:159], v132 offset:4608
	s_waitcnt lgkmcnt(0)
	v_mfma_f32_32x32x16_bf16 v[2:17], v[144:147], v[156:159], v[2:17]
	ds_read_b128 v[156:159], v132 offset:9216
	s_waitcnt lgkmcnt(0)
	v_mfma_f32_32x32x16_bf16 v[18:33], v[144:147], v[156:159], v[18:33]
	ds_read_b128 v[144:147], v132 offset:32
	ds_read_b128 v[156:159], v132 offset:4640
	s_waitcnt lgkmcnt(0)
	v_mfma_f32_32x32x16_bf16 v[2:17], v[144:147], v[156:159], v[2:17]
	ds_read_b128 v[156:159], v132 offset:9248
	s_waitcnt lgkmcnt(0)
	v_mfma_f32_32x32x16_bf16 v[18:33], v[144:147], v[156:159], v[18:33]
	ds_read_b128 v[144:147], v132 offset:64
	ds_read_b128 v[156:159], v132 offset:4672
	s_waitcnt lgkmcnt(0)
	v_mfma_f32_32x32x16_bf16 v[2:17], v[144:147], v[156:159], v[2:17]
	ds_read_b128 v[184:187], v132 offset:96
	ds_read_b128 v[156:159], v132 offset:4704
	s_waitcnt lgkmcnt(0)
	v_mfma_f32_32x32x16_bf16 v[2:17], v[184:187], v[156:159], v[2:17]
	ds_read_b128 v[156:159], v132 offset:9280
	ds_read_b128 v[188:191], v132 offset:9312
	s_waitcnt lgkmcnt(1)
	v_mfma_f32_32x32x16_bf16 v[18:33], v[144:147], v[156:159], v[18:33]
	s_nop 7
	v_mov_b32_e32 v176, v17
	v_mov_b32_e32 v146, v15
	v_mov_b32_e32 v178, v13
	v_mov_b32_e32 v180, v11
	v_mov_b32_e32 v144, v9
	v_mov_b32_e32 v152, v7
	v_mov_b32_e32 v148, v5
	s_waitcnt lgkmcnt(0)
	v_mfma_f32_32x32x16_bf16 v[18:33], v[184:187], v[188:191], v[18:33]
	v_mov_b32_e32 v156, v3
	s_nop 10
	v_mov_b32_e32 v177, v33
	v_mov_b32_e32 v17, v32
	v_mov_b32_e32 v147, v31
	v_mov_b32_e32 v15, v30
	v_mov_b32_e32 v179, v29
	v_mov_b32_e32 v13, v28
	v_mov_b32_e32 v181, v27
	v_mov_b32_e32 v11, v26
	v_mov_b32_e32 v145, v25
	v_mov_b32_e32 v9, v24
	v_mov_b32_e32 v153, v23
	v_mov_b32_e32 v7, v22
	v_mov_b32_e32 v149, v21
	v_mov_b32_e32 v5, v20
	v_mov_b32_e32 v157, v19
	v_mov_b32_e32 v34, v144
	v_mov_b32_e32 v35, v145
	v_mov_b32_e32 v36, v146
	v_mov_b32_e32 v37, v147
	v_mov_b32_e32 v38, v148
	v_mov_b32_e32 v39, v149
	v_mov_b32_e32 v40, v150
	v_mov_b32_e32 v41, v151
	v_mov_b32_e32 v42, v152
	v_mov_b32_e32 v43, v153
	v_mov_b32_e32 v44, v154
	v_mov_b32_e32 v45, v155
	v_mov_b32_e32 v46, v156
	v_mov_b32_e32 v47, v157
	v_mov_b32_e32 v48, v158
	v_mov_b32_e32 v49, v159
	v_mov_b32_e32 v50, v174
	v_mov_b32_e32 v51, v175
	v_mov_b32_e32 v52, v176
	v_mov_b32_e32 v53, v177
	v_mov_b32_e32 v54, v178
	v_mov_b32_e32 v55, v179
	v_mov_b32_e32 v56, v180
	v_mov_b32_e32 v57, v181
	v_mov_b32_e32 v58, v182
	v_mov_b32_e32 v59, v183
	v_mov_b32_e32 v60, v184
	v_mov_b32_e32 v61, v185
	v_mov_b32_e32 v62, v186
	v_mov_b32_e32 v63, v187
	v_mov_b32_e32 v64, v188
	v_mov_b32_e32 v65, v189
	v_mov_b32_e32 v66, v190
	v_mov_b32_e32 v67, v191
	v_mov_b32_e32 v68, v192
	v_mov_b32_e32 v69, v193
	v_mov_b32_e32 v70, v194
	v_mov_b32_e32 v71, v195
	v_mov_b32_e32 v72, v196
	v_mov_b32_e32 v73, v197
	v_mov_b32_e32 v74, v208
	v_mov_b32_e32 v75, v209
	v_mov_b32_e32 v76, v210
	v_mov_b32_e32 v77, v211
	v_mov_b32_e32 v78, v212
	v_mov_b32_e32 v79, v213
	v_mov_b32_e32 v80, v214
	v_mov_b32_e32 v81, v215
	v_mov_b32_e32 v82, v216
	v_mov_b32_e32 v83, v217
	v_mov_b32_e32 v84, v218
	v_mov_b32_e32 v85, v219
	v_mov_b32_e32 v86, v220
	v_mov_b32_e32 v87, v221
	v_mov_b32_e32 v88, v222
	v_mov_b32_e32 v89, v223
	v_mov_b32_e32 v90, v224
	v_mov_b32_e32 v91, v225
	v_mov_b32_e32 v92, v226
	v_mov_b32_e32 v93, v227
	v_mov_b32_e32 v94, v228
	v_mov_b32_e32 v95, v229
	v_mov_b32_e32 v96, v230
	v_mov_b32_e32 v97, v231
